# mLSTM scan: small per-chunk operands prefetched two chunks ahead with a second register set (256 VGPRs)
# baseline (speedup 1.0000x reference)
.LBB0_451:
	s_add_i32 s18, s34, 64
	s_sub_i32 s19, 0xfbf, s34
	s_and_b64 s[16:17], s[2:3], exec
	s_cselect_b32 s16, s18, s19
	s_ashr_i32 s17, s16, 31
	s_lshl_b64 s[16:17], s[16:17], 12
	s_sub_i32 s18, 0xfbf, s51
	s_add_i32 s19, s34, 0x41
	global_load_dword v48, v[24:25], off offset:32
	v_lshl_add_u64 v[24:25], v[64:65], 0, s[16:17]
	s_and_b64 s[16:17], s[2:3], exec
	s_cselect_b32 s16, s19, s18
	s_ashr_i32 s17, s16, 31
	s_lshl_b64 s[16:17], s[16:17], 12
	s_sub_i32 s18, 0xfbf, s63
	s_add_i32 s19, s34, 0x42
	v_lshl_add_u64 v[28:29], v[64:65], 0, s[16:17]
	s_and_b64 s[16:17], s[2:3], exec
	s_cselect_b32 s16, s19, s18
	s_ashr_i32 s17, s16, 31
	s_lshl_b64 s[16:17], s[16:17], 12
	s_sub_i32 s18, 0xfbf, s62
	s_add_i32 s19, s34, 0x43
	v_lshl_add_u64 v[30:31], v[64:65], 0, s[16:17]
	s_and_b64 s[16:17], s[2:3], exec
	s_cselect_b32 s16, s19, s18
	s_ashr_i32 s17, s16, 31
	s_lshl_b64 s[16:17], s[16:17], 12
	s_sub_i32 s18, 0xfbf, s60
	s_add_i32 s19, s34, 0x44
	v_lshl_add_u64 v[32:33], v[64:65], 0, s[16:17]
	s_and_b64 s[16:17], s[2:3], exec
	s_cselect_b32 s16, s19, s18
	s_ashr_i32 s17, s16, 31
	s_lshl_b64 s[16:17], s[16:17], 12
	s_sub_i32 s18, 0xfbf, s59
	s_add_i32 s19, s34, 0x45
	global_load_dword v151, v[24:25], off
	global_load_dword v152, v[24:25], off offset:2048
	global_load_dword v153, v[28:29], off
	global_load_dword v154, v[28:29], off offset:2048
	global_load_dword v157, v[30:31], off
	global_load_dword v158, v[30:31], off offset:2048
	global_load_dword v159, v[32:33], off
	global_load_dword v160, v[32:33], off offset:2048
	v_lshl_add_u64 v[24:25], v[64:65], 0, s[16:17]
	s_and_b64 s[16:17], s[2:3], exec
	s_cselect_b32 s16, s19, s18
	s_ashr_i32 s17, s16, 31
	s_lshl_b64 s[16:17], s[16:17], 12
	s_sub_i32 s18, 0xfbf, s58
	s_add_i32 s19, s34, 0x46
	v_lshl_add_u64 v[28:29], v[64:65], 0, s[16:17]
	s_and_b64 s[16:17], s[2:3], exec
	s_cselect_b32 s16, s19, s18
	s_ashr_i32 s17, s16, 31
	s_lshl_b64 s[16:17], s[16:17], 12
	s_sub_i32 s18, 0xfbf, s57
	s_add_i32 s19, s34, 0x47
	v_lshl_add_u64 v[30:31], v[64:65], 0, s[16:17]
	s_and_b64 s[16:17], s[2:3], exec
	s_cselect_b32 s16, s19, s18
	s_ashr_i32 s17, s16, 31
	s_lshl_b64 s[16:17], s[16:17], 12
	s_sub_i32 s18, 0xfbf, s56
	s_add_i32 s19, s34, 0x48
	v_lshl_add_u64 v[32:33], v[64:65], 0, s[16:17]
	s_and_b64 s[16:17], s[2:3], exec
	s_cselect_b32 s16, s19, s18
	s_ashr_i32 s17, s16, 31
	s_lshl_b64 s[16:17], s[16:17], 12
	s_sub_i32 s18, 0xfbf, s55
	s_add_i32 s19, s34, 0x49
	global_load_dword v161, v[24:25], off
	global_load_dword v162, v[24:25], off offset:2048
	global_load_dword v164, v[28:29], off
	global_load_dword v165, v[28:29], off offset:2048
	global_load_dword v169, v[30:31], off
	global_load_dword v171, v[30:31], off offset:2048
	global_load_dword v180, v[32:33], off
	global_load_dword v181, v[32:33], off offset:2048
	v_lshl_add_u64 v[24:25], v[64:65], 0, s[16:17]
	s_and_b64 s[16:17], s[2:3], exec
	s_cselect_b32 s16, s19, s18
	s_ashr_i32 s17, s16, 31
	s_lshl_b64 s[16:17], s[16:17], 12
	s_sub_i32 s18, 0xfbf, s54
	s_add_i32 s19, s34, 0x4a
	v_lshl_add_u64 v[28:29], v[64:65], 0, s[16:17]
	s_and_b64 s[16:17], s[2:3], exec
	s_cselect_b32 s16, s19, s18
	s_ashr_i32 s17, s16, 31
	s_lshl_b64 s[16:17], s[16:17], 12
	s_sub_i32 s18, 0xfbf, s53
	s_add_i32 s19, s34, 0x4b
	v_lshl_add_u64 v[30:31], v[64:65], 0, s[16:17]
	s_and_b64 s[16:17], s[2:3], exec
	s_cselect_b32 s16, s19, s18
	s_ashr_i32 s17, s16, 31
	s_lshl_b64 s[16:17], s[16:17], 12
	s_sub_i32 s18, 0xfbf, s52
	s_add_i32 s19, s34, 0x4c
	v_lshl_add_u64 v[32:33], v[64:65], 0, s[16:17]
	s_and_b64 s[16:17], s[2:3], exec
	s_cselect_b32 s16, s19, s18
	s_ashr_i32 s17, s16, 31
	s_lshl_b64 s[16:17], s[16:17], 12
	s_sub_i32 s18, 0xfbf, s50
	s_add_i32 s19, s34, 0x4d
	global_load_dword v190, v[24:25], off
	global_load_dword v191, v[24:25], off offset:2048
	global_load_dword v192, v[28:29], off
	global_load_dword v193, v[28:29], off offset:2048
	global_load_dword v194, v[30:31], off
	global_load_dword v195, v[30:31], off offset:2048
	global_load_dword v196, v[32:33], off
	global_load_dword v197, v[32:33], off offset:2048
	v_lshl_add_u64 v[24:25], v[64:65], 0, s[16:17]
	s_and_b64 s[16:17], s[2:3], exec
	s_cselect_b32 s16, s19, s18
	s_ashr_i32 s17, s16, 31
	s_lshl_b64 s[16:17], s[16:17], 12
	s_sub_i32 s18, 0xfbf, s48
	s_add_i32 s19, s34, 0x4e
	v_lshl_add_u64 v[28:29], v[64:65], 0, s[16:17]
	s_and_b64 s[16:17], s[2:3], exec
	s_cselect_b32 s16, s19, s18
	s_ashr_i32 s17, s16, 31
	s_lshl_b64 s[16:17], s[16:17], 12
	s_sub_i32 s18, 0xfbf, s47
	s_add_i32 s19, s34, 0x4f
	v_lshl_add_u64 v[30:31], v[64:65], 0, s[16:17]
	s_and_b64 s[16:17], s[2:3], exec
	s_cselect_b32 s16, s19, s18
	s_ashr_i32 s17, s16, 31
	s_lshl_b64 s[16:17], s[16:17], 12
	v_lshl_add_u64 v[32:33], v[64:65], 0, s[16:17]
	global_load_dword v198, v[24:25], off
	global_load_dword v199, v[24:25], off offset:2048
	global_load_dword v200, v[28:29], off
	global_load_dword v201, v[28:29], off offset:2048
	global_load_dword v202, v[30:31], off
	global_load_dword v203, v[30:31], off offset:2048
	global_load_dword v204, v[32:33], off
	global_load_dword v205, v[32:33], off offset:2048
	v_xor_b32_e32 v0, v26, v63
	v_lshl_add_u32 v166, v0, 4, v73
	v_lshlrev_b32_e32 v0, 1, v56
	v_and_b32_e32 v24, 64, v108
	v_lshl_add_u64 v[68:69], s[6:7], 0, v[0:1]
	s_and_b32 s6, s34, 48
	v_or_b32_e32 v0, s34, v50
	v_or3_b32 v27, s6, v58, v24
	s_lshr_b32 s6, s35, 1
	s_lshl_b32 s16, s46, 1
	v_mul_lo_u32 v25, v0, s78
	v_lshl_or_b32 v26, s49, 4, v50
	v_mul_lo_u32 v28, v0, s37
	v_mov_b32_e32 v0, s75
	s_and_b32 s6, s6, 0xfffffe0
	s_andn2_b32 s35, s35, 63
	v_mad_u32_u24 v168, v26, s37, v0
	v_or_b32_e32 v0, v24, v75
	v_or_b32_e32 v24, s6, v50
	s_and_b64 s[6:7], s[2:3], exec
	s_cselect_b32 s6, s77, s33
	s_cselect_b32 s7, s76, s36
	s_lshl_b64 s[4:5], s[4:5], 1
	s_add_u32 s4, s7, s4
	s_addc_u32 s5, s6, s5
	s_lshl_b32 s6, s15, 1
	s_add_u32 s4, s4, s6
	s_addc_u32 s5, s5, 0
	v_lshl_add_u32 v163, v23, 1, 0
	s_movk_i32 s17, 0x8e
	s_add_u32 s4, s4, s14
	v_mad_u32_u24 v23, v23, s17, v163
	v_lshlrev_b32_e32 v170, 2, v0
	v_xor_b32_e32 v0, s16, v63
	s_addc_u32 s5, s5, 0
	s_lshl_b32 s6, s49, 5
	v_lshl_add_u32 v173, v0, 4, v23
	v_bitop3_b32 v0, s16, v63, 1 bitop3:0x36
	s_add_u32 s4, s4, s6
	v_lshl_add_u32 v174, v0, 4, v23
	s_addc_u32 s5, s5, 0
	v_lshlrev_b32_e32 v0, 1, v50
	v_add_u32_e32 v172, s35, v78
	v_lshlrev_b32_e32 v176, 2, v27
	v_lshl_add_u64 v[70:71], s[4:5], 0, v[0:1]
	v_mul_lo_u32 v0, v24, s37
	s_mov_b32 s18, 0
	s_mov_b32 s19, 2
	v_mul_u32_u24_e32 v167, 0x210, v26
	s_mul_i32 s20, s46, 0x2100
	s_mul_i32 s21, s51, 0x210
	v_not_b32_e32 v175, v127
	v_or_b32_e32 v177, 4, v176
	v_or_b32_e32 v178, 8, v176
	v_or_b32_e32 v179, 12, v176
	v_add_u32_e32 v0, 0, v0
	s_sub_i32 s24, 0, s34
	v_or_b32_e32 v182, s6, v74
	v_add_u32_e32 v183, s34, v58
	v_subrev_u32_e32 v184, s34, v104
	v_subrev_u32_e32 v185, s34, v83
	v_subrev_u32_e32 v186, s6, v106
	s_mov_b32 s25, 62
	v_add_u32_e32 v187, v99, v25
	v_add_u32_e32 v188, v76, v28
	v_add_u32_e32 v189, v172, v85
	s_mov_b32 s26, 0
	v_mov_b32_e32 v23, v22
	v_mov_b32_e32 v24, v22
	v_mov_b32_e32 v25, v22
	v_mov_b32_e32 v30, v22
	v_mov_b32_e32 v31, v22
	v_mov_b32_e32 v32, v22
	v_mov_b32_e32 v33, v22
	v_mov_b32_e32 v26, v22
	v_mov_b32_e32 v27, v22
	v_mov_b32_e32 v28, v22
	v_mov_b32_e32 v29, v22
	v_mov_b32_e32 v34, v22
	v_mov_b32_e32 v35, v22
	v_mov_b32_e32 v36, v22
	v_mov_b32_e32 v37, v22
	v_mov_b32_e32 v38, v22
	v_mov_b32_e32 v39, v22
	v_mov_b32_e32 v40, v22
	v_mov_b32_e32 v41, v22
	v_mov_b32_e32 v42, v22
	v_mov_b32_e32 v43, v22
	v_mov_b32_e32 v44, v22
	v_mov_b32_e32 v45, v22
	v_readfirstlane_b32 s58, v64
	v_readfirstlane_b32 s59, v65
	s_lshr_b32 s36, s35, 6
	s_and_b32 s36, s36, 1
	s_lshl_b32 s36, s36, 8
	s_sub_u32 s58, s58, s36
	s_subb_u32 s59, s59, 0
	v_lshlrev_b32_e32 v89, 2, v220
	v_add_u32_e32 v89, s36, v89
	s_cmp_eq_u32 s61, 0
	s_cselect_b32 s57, 0, -1
	s_xor_b32 s56, s57, 0x40000
	s_sub_i32 s56, s56, s57
	s_xor_b32 s36, s57, 0x2000
	s_sub_i32 s36, s36, s57
	s_and_b32 s37, s57, 0xe000
	s_and_b32 s40, s57, 0x1000
	s_andn2_b32 s41, 0x1000, s57
	s_add_i32 s38, s34, 0x80
	s_sub_i32 s39, 0xf70, s34
	s_cmp_eq_u32 s61, 0
	s_cselect_b32 s38, s38, s39
	s_lshl_b32 s38, s38, 12
	s_add_u32 s58, s58, s38
	s_addc_u32 s59, s59, 0
	s_add_u32 s52, s58, s40
	s_addc_u32 s53, s59, 0
	s_add_u32 s54, s58, s41
	s_addc_u32 s55, s59, 0
	v_add_u32_e32 v89, s37, v89
	v_add_u32_e32 v90, s36, v89
	v_add_u32_e32 v91, s36, v90
	v_add_u32_e32 v92, s36, v91
	v_add_u32_e32 v93, s36, v92
	v_add_u32_e32 v94, s36, v93
	v_add_u32_e32 v95, s36, v94
	v_add_u32_e32 v96, s36, v95
	v_readfirstlane_b32 s36, v68
	v_readfirstlane_b32 s37, v69
	s_cmp_eq_u32 s61, 0
	s_cselect_b32 s58, 64, 0xf80
	s_mul_i32 s59, s58, 0x4800
	s_add_u32 s36, s36, s59
	s_addc_u32 s37, s37, 0
	s_lshl_b32 s59, s58, 6
	s_add_u32 s38, s8, s59
	s_addc_u32 s39, s9, 0
	s_xor_b32 s40, s57, 0x120000
	s_sub_i32 s40, s40, s57
	s_xor_b32 s41, s57, 0x1000
	s_sub_i32 s41, s41, s57
	s_and_b32 s58, s57, 64
	s_xor_b32 s59, s57, 0x4800
	s_sub_i32 s59, s59, s57
	s_xor_b32 s60, s57, 64
	s_sub_i32 s60, s60, s57
	v_xor_b32_e32 v73, s57, v182
	v_add_u32_e32 v73, s58, v73
	v_mul_u32_u24_e32 v97, 0x4800, v73
	v_lshl_add_u32 v97, v50, 2, v97
	v_lshlrev_b32_e32 v50, 6, v73
	v_add_u32_e32 v98, s59, v97
	v_add_u32_e32 v99, s59, v98
	v_add_u32_e32 v100, s59, v99
	v_add_u32_e32 v101, s59, v100
	v_add_u32_e32 v102, s59, v101
	v_add_u32_e32 v103, s59, v102
	v_add_u32_e32 v104, s59, v103
	v_add_u32_e32 v51, s60, v50
	v_add_u32_e32 v52, s60, v51
	v_add_u32_e32 v53, s60, v52
	v_add_u32_e32 v54, s60, v53
	v_add_u32_e32 v55, s60, v54
	v_add_u32_e32 v56, s60, v55
	v_add_u32_e32 v57, s60, v56
	v_xor_b32_e32 v73, s57, v220
	v_add_u32_e32 v73, s58, v73
	v_lshlrev_b32_e32 v73, 6, v73
	s_and_b64 vcc, exec, s[10:11]
	s_cbranch_vccz .Lml_pro_skip
	global_load_dword v127, v97, s[36:37] nt
	global_load_dword v58, v50, s[38:39]
	global_load_dword v128, v98, s[36:37] nt
	global_load_dword v59, v51, s[38:39]
	global_load_dword v129, v99, s[36:37] nt
	global_load_dword v60, v52, s[38:39]
	global_load_dword v130, v100, s[36:37] nt
	global_load_dword v62, v53, s[38:39]
	global_load_dword v131, v101, s[36:37] nt
	global_load_dword v63, v54, s[38:39]
	global_load_dword v132, v102, s[36:37] nt
	global_load_dword v64, v55, s[38:39]
	global_load_dword v133, v103, s[36:37] nt
	global_load_dword v65, v56, s[38:39]
	global_load_dword v175, v104, s[36:37] nt
	global_load_dword v68, v57, s[38:39]
.Lml_pro_skip:
	s_cmp_eq_u32 s61, 0
	s_cselect_b32 s58, 1, 62
	s_lshl_b32 s58, s58, 14
	s_mov_b32 s59, 0
	v_lshl_add_u64 v[46:47], v[66:67], 0, s[58:59]
	global_load_dwordx4 v[252:255], v[46:47], off
	global_load_dword v69, v73, s[38:39]
	global_load_dword v207, v73, s[38:39] offset:32
	s_add_u32 s36, s36, s40
	s_addc_u32 s37, s37, s57
	s_add_u32 s38, s38, s41
	s_addc_u32 s39, s39, s57
	s_and_b64 vcc, exec, s[10:11]
	s_cbranch_vccnz .Lml_wpro_a
	s_waitcnt vmcnt(35)
	s_branch .Lml_wpro_b
.Lml_wpro_a:
	s_waitcnt vmcnt(51)
.Lml_wpro_b:
	s_branch .LBB0_453

.LBB0_453:
	s_and_b64 vcc, exec, s[10:11]
	s_cbranch_vccnz .Lml_wh1_a
	s_waitcnt vmcnt(39)
	s_branch .Lml_wh1_b
.Lml_wh1_a:
	s_waitcnt vmcnt(55)
.Lml_wh1_b:
	ds_bpermute_b32 v224, v109, v48
	v_cndmask_b32_e64 v46, 0, 1, s[12:13]
	v_cmp_ne_u32_e64 s[4:5], 1, v46
	s_andn2_b64 vcc, exec, s[12:13]
	s_cbranch_vccnz .LBB0_455
	v_cvt_pk_bf16_f32 v46, v148, s0
	ds_write_b16 v72, v46 offset:4608

.LBB0_461:
	s_add_i32 s28, s19, -1
	s_add_i32 s16, s25, -1
	s_and_b64 s[30:31], s[2:3], exec
	s_cselect_b32 s16, s19, s16
	s_max_i32 s16, s16, 0
	s_mov_b32 s17, s22
	s_lshl_b64 s[16:17], s[16:17], 14
	v_lshl_add_u64 v[18:19], v[66:67], 0, s[16:17]
	global_load_dwordx4 v[18:21], v[18:19], off
	global_load_dword v148, v73, s[38:39]
.LBB0_463:
	s_mov_b64 s[62:63], s[38:39]
	s_add_u32 s36, s36, s40
	s_addc_u32 s37, s37, s57
	s_add_u32 s38, s38, s41
	s_addc_u32 s39, s39, s57
	s_waitcnt lgkmcnt(0)
	s_barrier
	ds_read_b128 v[226:229], v187
	v_add_u32_e32 v46, v79, v167
	ds_read_b128 v[230:233], v46
	ds_read_b128 v[234:237], v80
	s_waitcnt lgkmcnt(1)
	v_mfma_f32_16x16x32_bf16 v[230:233], v[226:229], v[230:233], 0
	global_load_dword v113, v89, s[52:53]
	s_waitcnt lgkmcnt(0)
	v_mfma_f32_16x16x32_bf16 v[226:229], v[226:229], v[234:237], 0
	global_load_dword v114, v89, s[52:53] offset:2048
	ds_read_b128 v[234:237], v187 offset:64
	ds_read_b128 v[238:241], v46 offset:64
	s_waitcnt lgkmcnt(0)
	v_mfma_f32_16x16x32_bf16 v[230:233], v[234:237], v[238:241], v[230:233]
	global_load_dword v115, v89, s[54:55]
	ds_read_b128 v[238:241], v80 offset:64
	s_waitcnt lgkmcnt(0)
	v_mfma_f32_16x16x32_bf16 v[226:229], v[234:237], v[238:241], v[226:229]
	global_load_dword v116, v89, s[54:55] offset:2048
	ds_read_b128 v[234:237], v187 offset:128
	ds_read_b128 v[238:241], v46 offset:128
	s_waitcnt lgkmcnt(0)
	v_mfma_f32_16x16x32_bf16 v[230:233], v[234:237], v[238:241], v[230:233]
	global_load_dword v117, v90, s[52:53]
	ds_read_b128 v[238:241], v80 offset:128
	s_waitcnt lgkmcnt(0)
	v_mfma_f32_16x16x32_bf16 v[226:229], v[234:237], v[238:241], v[226:229]
	global_load_dword v118, v90, s[52:53] offset:2048
	ds_read_b128 v[234:237], v187 offset:192
	ds_read_b128 v[238:241], v46 offset:192
	s_waitcnt lgkmcnt(0)
	v_mfma_f32_16x16x32_bf16 v[230:233], v[234:237], v[238:241], v[230:233]
	global_load_dword v119, v90, s[54:55]
	ds_read_b128 v[238:241], v80 offset:192
	s_waitcnt lgkmcnt(0)
	v_mfma_f32_16x16x32_bf16 v[226:229], v[234:237], v[238:241], v[226:229]
	global_load_dword v120, v90, s[54:55] offset:2048
	ds_read_b128 v[234:237], v187 offset:256
	ds_read_b128 v[238:241], v46 offset:256
	s_waitcnt lgkmcnt(0)
	v_mfma_f32_16x16x32_bf16 v[230:233], v[234:237], v[238:241], v[230:233]
	global_load_dword v121, v91, s[52:53]
	ds_read_b128 v[238:241], v80 offset:256
	s_waitcnt lgkmcnt(0)
	v_mfma_f32_16x16x32_bf16 v[226:229], v[234:237], v[238:241], v[226:229]
	global_load_dword v122, v91, s[52:53] offset:2048
	ds_read_b128 v[234:237], v187 offset:320
	ds_read_b128 v[238:241], v46 offset:320
	s_waitcnt lgkmcnt(0)
	v_mfma_f32_16x16x32_bf16 v[230:233], v[234:237], v[238:241], v[230:233]
	global_load_dword v123, v91, s[54:55]
	ds_read_b128 v[238:241], v80 offset:320
	s_waitcnt lgkmcnt(0)
	v_mfma_f32_16x16x32_bf16 v[226:229], v[234:237], v[238:241], v[226:229]
	global_load_dword v124, v91, s[54:55] offset:2048
	ds_read_b128 v[234:237], v187 offset:384
	ds_read_b128 v[238:241], v46 offset:384
	s_waitcnt lgkmcnt(0)
	v_mfma_f32_16x16x32_bf16 v[230:233], v[234:237], v[238:241], v[230:233]
	global_load_dword v125, v92, s[52:53]
	ds_read_b128 v[238:241], v80 offset:384
	s_waitcnt lgkmcnt(0)
	v_mfma_f32_16x16x32_bf16 v[226:229], v[234:237], v[238:241], v[226:229]
	global_load_dword v126, v92, s[52:53] offset:2048
	ds_read_b128 v[234:237], v187 offset:448
	ds_read_b128 v[238:241], v46 offset:448
	s_waitcnt lgkmcnt(0)
	v_mfma_f32_16x16x32_bf16 v[230:233], v[234:237], v[238:241], v[230:233]
	global_load_dword v134, v92, s[54:55]
	ds_read_b128 v[238:241], v80 offset:448
	s_waitcnt lgkmcnt(0)
	v_mfma_f32_16x16x32_bf16 v[226:229], v[234:237], v[238:241], v[226:229]
	global_load_dword v135, v92, s[54:55] offset:2048
	ds_bpermute_b32 v46, v176, v48
	v_add_u32_e32 v206, v77, v75
	v_add_u32_e32 v217, s18, v183
	s_waitcnt lgkmcnt(0)
	v_mul_f32_e32 v46, 0x3fb8aa3b, v46
	v_exp_f32_e32 v218, v46
	ds_bpermute_b32 v46, v177, v48
	s_waitcnt lgkmcnt(0)
	v_mul_f32_e32 v46, 0x3fb8aa3b, v46
	v_exp_f32_e32 v219, v46
	ds_bpermute_b32 v46, v178, v48
	v_pk_mul_f32 v[226:227], v[226:227], v[218:219]
	s_waitcnt lgkmcnt(0)
	v_mul_f32_e32 v46, 0x3fb8aa3b, v46
	v_exp_f32_e32 v222, v46
	ds_bpermute_b32 v46, v179, v48
	s_waitcnt lgkmcnt(0)
	v_mul_f32_e32 v46, 0x3fb8aa3b, v46
	v_exp_f32_e32 v223, v46
	v_pk_mul_f32 v[46:47], v[230:231], v[218:219]
	v_add_u32_e32 v218, v168, v81
	ds_read_b128 v[234:237], v218
	v_pk_mul_f32 v[48:49], v[232:233], v[222:223]
	ds_read_b128 v[230:233], v188
	v_pk_mul_f32 v[228:229], v[228:229], v[222:223]
	v_add_u32_e32 v219, v168, v82
	v_add_u32_e32 v222, s26, v185
	s_waitcnt lgkmcnt(0)
	v_mfma_f32_16x16x32_bf16 v[46:49], v[230:233], v[234:237], v[46:49]
	global_load_dword v136, v93, s[52:53]
	ds_read_b128 v[234:237], v206
	s_waitcnt lgkmcnt(0)
	v_mfma_f32_16x16x32_bf16 v[226:229], v[230:233], v[234:237], v[226:229]
	global_load_dword v137, v93, s[52:53] offset:2048
	ds_read_b128 v[230:233], v188 offset:64
	ds_read_b128 v[234:237], v219
	s_waitcnt lgkmcnt(0)
	v_mfma_f32_16x16x32_bf16 v[46:49], v[230:233], v[234:237], v[46:49]
	global_load_dword v138, v93, s[54:55]
	ds_read_b128 v[234:237], v110
	s_waitcnt lgkmcnt(0)
	v_mfma_f32_16x16x32_bf16 v[226:229], v[230:233], v[234:237], v[226:229]
	global_load_dword v139, v93, s[54:55] offset:2048
	v_cndmask_b32_e64 v230, v222, v217, s[2:3]
	v_ashrrev_i32_e32 v231, 31, v230
	v_lshlrev_b64 v[230:231], 12, v[230:231]
	s_nop 4
	ds_bpermute_b32 v223, v170, v226
	v_lshl_add_u64 v[230:231], v[70:71], 0, v[230:231]
	s_waitcnt lgkmcnt(0)
	v_max_f32_e64 v223, |v223|, |v223|
	v_max_f32_e32 v223, 1.0, v223
	v_div_scale_f32 v225, s[16:17], v223, v223, v46
	v_rcp_f32_e32 v226, v225
	s_nop 0
	v_fma_f32 v232, -v225, v226, 1.0
	v_fmac_f32_e32 v226, v232, v226
	v_div_scale_f32 v232, vcc, v46, v223, v46
	v_mul_f32_e32 v233, v232, v226
	v_fma_f32 v234, -v225, v233, v232
	v_fmac_f32_e32 v233, v234, v226
	v_fma_f32 v225, -v225, v233, v232
	v_div_fmas_f32 v225, v225, v226, v233
	v_div_fixup_f32 v46, v225, v223, v46
	v_cvt_pk_bf16_f32 v46, v46, s0
	global_store_short v[230:231], v46, off offset:2048
	ds_bpermute_b32 v46, v170, v227
	v_add_u32_e32 v223, -1, v222
	v_add_u32_e32 v225, 1, v217
	v_cndmask_b32_e64 v226, v223, v225, s[2:3]
	v_ashrrev_i32_e32 v227, 31, v226
	s_waitcnt lgkmcnt(0)
	v_max_f32_e64 v46, |v46|, |v46|
	v_max_f32_e32 v46, 1.0, v46
	v_div_scale_f32 v223, s[16:17], v46, v46, v47
	v_rcp_f32_e32 v225, v223
	s_nop 0
	v_fma_f32 v230, -v223, v225, 1.0
	v_fmac_f32_e32 v225, v230, v225
	v_div_scale_f32 v230, vcc, v47, v46, v47
	v_mul_f32_e32 v231, v230, v225
	v_fma_f32 v232, -v223, v231, v230
	v_fmac_f32_e32 v231, v232, v225
	v_fma_f32 v223, -v223, v231, v230
	v_div_fmas_f32 v223, v223, v225, v231
	ds_bpermute_b32 v225, v170, v228
	v_div_fixup_f32 v46, v223, v46, v47
	v_cvt_pk_bf16_f32 v223, v46, s0
	v_lshlrev_b64 v[46:47], 12, v[226:227]
	v_lshl_add_u64 v[46:47], v[70:71], 0, v[46:47]
	s_waitcnt lgkmcnt(0)
	v_max_f32_e64 v225, |v225|, |v225|
	v_max_f32_e32 v225, 1.0, v225
	v_div_scale_f32 v226, s[16:17], v225, v225, v48
	v_rcp_f32_e32 v227, v226
	global_store_short v[46:47], v223, off offset:2048
	v_add_u32_e32 v223, s26, v184
	v_add_u32_e32 v46, 0xffd, v223
	v_fma_f32 v228, -v226, v227, 1.0
	v_fmac_f32_e32 v227, v228, v227
	v_div_scale_f32 v228, vcc, v48, v225, v48
	v_mul_f32_e32 v230, v228, v227
	v_fma_f32 v231, -v226, v230, v228
	v_add_u32_e32 v47, 2, v217
	v_fmac_f32_e32 v230, v231, v227
	v_cndmask_b32_e64 v46, v46, v47, s[2:3]
	v_fma_f32 v226, -v226, v230, v228
	v_ashrrev_i32_e32 v47, 31, v46
	v_div_fmas_f32 v226, v226, v227, v230
	v_div_fixup_f32 v48, v226, v225, v48
	v_lshlrev_b64 v[46:47], 12, v[46:47]
	v_cvt_pk_bf16_f32 v48, v48, s0
	v_lshl_add_u64 v[46:47], v[70:71], 0, v[46:47]
	global_store_short v[46:47], v48, off offset:2048
	ds_bpermute_b32 v48, v170, v229
	v_add_u32_e32 v46, 0xffc, v223
	v_add_u32_e32 v47, 3, v217
	v_cndmask_b32_e64 v46, v46, v47, s[2:3]
	v_ashrrev_i32_e32 v47, 31, v46
	s_waitcnt lgkmcnt(0)
	v_max_f32_e64 v48, |v48|, |v48|
	v_max_f32_e32 v48, 1.0, v48
	v_div_scale_f32 v225, s[16:17], v48, v48, v49
	v_rcp_f32_e32 v226, v225
	v_lshlrev_b64 v[46:47], 12, v[46:47]
	v_lshl_add_u64 v[46:47], v[70:71], 0, v[46:47]
	v_fma_f32 v227, -v225, v226, 1.0
	v_fmac_f32_e32 v226, v227, v226
	v_div_scale_f32 v227, vcc, v49, v48, v49
	v_mul_f32_e32 v228, v227, v226
	v_fma_f32 v229, -v225, v228, v227
	v_fmac_f32_e32 v228, v229, v226
	v_fma_f32 v225, -v225, v228, v227
	v_div_fmas_f32 v225, v225, v226, v228
	v_div_fixup_f32 v48, v225, v48, v49
	v_cvt_pk_bf16_f32 v48, v48, s0
	global_store_short v[46:47], v48, off offset:2048
	v_mul_f32_e32 v46, 0x3fb8aa3b, v224
	v_add_u32_e32 v224, v0, v81
	v_exp_f32_e32 v46, v46
	ds_read_b128 v[226:229], v224 offset:33792
	ds_read_b128 v[230:233], v111
	v_add_u32_e32 v49, v0, v82
	v_add_u32_e32 v225, v84, v82
	v_pk_mul_f32 v[44:45], v[44:45], v[46:47] op_sel_hi:[1,0]
	v_pk_mul_f32 v[42:43], v[42:43], v[46:47] op_sel_hi:[1,0]
	v_pk_mul_f32 v[40:41], v[40:41], v[46:47] op_sel_hi:[1,0]
	v_pk_mul_f32 v[38:39], v[38:39], v[46:47] op_sel_hi:[1,0]
	s_waitcnt lgkmcnt(0)
	v_mfma_f32_16x16x32_bf16 v[42:45], v[226:229], v[230:233], v[42:45]
	global_load_dword v140, v94, s[52:53]
	ds_read_b128 v[226:229], v49 offset:33792
	ds_read_b128 v[230:233], v225
	v_pk_mul_f32 v[36:37], v[36:37], v[46:47] op_sel_hi:[1,0]
	s_waitcnt lgkmcnt(0)
	v_mfma_f32_16x16x32_bf16 v[42:45], v[226:229], v[230:233], v[42:45]
	global_load_dword v141, v94, s[52:53] offset:2048
	v_mul_f32_e64 v34, v34, v46
	v_mul_f32_e64 v35, v35, v46
	s_nop 5
	v_cvt_pk_bf16_f32 v226, v42, v43
	v_cvt_pk_bf16_f32 v227, v44, v45
	ds_write_b64 v189, v[226:227] offset:17952
	v_add_u32_e32 v226, v86, v81
	ds_read_b128 v[228:231], v49 offset:33792
	ds_read_b128 v[232:235], v224 offset:33792
	ds_read_b128 v[236:239], v226
	v_add_u32_e32 v227, v86, v82
	s_waitcnt lgkmcnt(0)
	v_mfma_f32_16x16x32_bf16 v[38:41], v[232:235], v[236:239], v[38:41]
	global_load_dword v142, v94, s[54:55]
	ds_read_b128 v[232:235], v227
	s_waitcnt lgkmcnt(0)
	v_mfma_f32_16x16x32_bf16 v[38:41], v[228:231], v[232:235], v[38:41]
	global_load_dword v143, v94, s[54:55] offset:2048
	s_nop 7
	v_cvt_pk_bf16_f32 v228, v38, v39
	v_cvt_pk_bf16_f32 v229, v40, v41
	ds_write_b64 v189, v[228:229] offset:26400
	ds_read_b128 v[228:231], v49 offset:33792
	ds_read_b128 v[232:235], v224 offset:33792
	ds_read_b128 v[236:239], v206
	s_waitcnt lgkmcnt(0)
	v_mfma_f32_16x16x32_bf16 v[34:37], v[232:235], v[236:239], v[34:37]
	global_load_dword v144, v95, s[52:53]
	ds_read_b128 v[232:235], v110
	s_waitcnt lgkmcnt(0)
	v_mfma_f32_16x16x32_bf16 v[34:37], v[228:231], v[232:235], v[34:37]
	global_load_dword v145, v95, s[52:53] offset:2048
	s_and_saveexec_b64 s[16:17], s[0:1]
	s_nop 6
	v_cvt_pk_bf16_f32 v228, v34, v35
	v_cvt_pk_bf16_f32 v229, v36, v37
	ds_write_b64 v172, v[228:229] offset:34848
	s_or_b64 exec, exec, s[16:17]
	ds_read_b128 v[228:231], v224 offset:36096
	ds_read_b128 v[232:235], v111
	ds_read_b128 v[236:239], v49 offset:36096
	v_mov_b32_e32 v47, v46
	v_mov_b32_e32 v240, v46
	v_mov_b32_e32 v241, v46
	v_pk_mul_f32 v[28:29], v[28:29], v[240:241]
	v_pk_mul_f32 v[26:27], v[26:27], v[46:47]
	v_pk_mul_f32 v[32:33], v[32:33], v[240:241]
	v_pk_mul_f32 v[30:31], v[30:31], v[46:47]
	s_waitcnt lgkmcnt(1)
	v_mfma_f32_16x16x32_bf16 v[26:29], v[228:231], v[232:235], v[26:29]
	global_load_dword v146, v95, s[54:55]
	ds_read_b128 v[228:231], v225
	v_pk_mul_f32 v[24:25], v[24:25], v[240:241]
	v_pk_mul_f32 v[22:23], v[22:23], v[46:47]
	s_waitcnt lgkmcnt(0)
	v_mfma_f32_16x16x32_bf16 v[26:29], v[236:239], v[228:231], v[26:29]
	global_load_dword v147, v95, s[54:55] offset:2048
	s_nop 7
	v_cvt_pk_bf16_f32 v228, v26, v27
	v_cvt_pk_bf16_f32 v229, v28, v29
	ds_write_b64 v189, v[228:229] offset:17984
	ds_read_b128 v[228:231], v224 offset:36096
	ds_read_b128 v[232:235], v226
	ds_read_b128 v[236:239], v227
	s_waitcnt lgkmcnt(1)
	v_mfma_f32_16x16x32_bf16 v[30:33], v[228:231], v[232:235], v[30:33]
	global_load_dword v149, v96, s[52:53]
	ds_read_b128 v[228:231], v49 offset:36096
	s_waitcnt lgkmcnt(0)
	v_mfma_f32_16x16x32_bf16 v[30:33], v[228:231], v[236:239], v[30:33]
	global_load_dword v150, v96, s[52:53] offset:2048
	s_nop 7
	v_cvt_pk_bf16_f32 v228, v30, v31
	v_cvt_pk_bf16_f32 v229, v32, v33
	ds_write_b64 v189, v[228:229] offset:26432
	ds_read_b128 v[228:231], v224 offset:36096
	ds_read_b128 v[232:235], v206
	ds_read_b128 v[236:239], v110
	s_waitcnt lgkmcnt(1)
	v_mfma_f32_16x16x32_bf16 v[22:25], v[228:231], v[232:235], v[22:25]
	global_load_dword v155, v96, s[54:55]
	ds_read_b128 v[228:231], v49 offset:36096
	s_waitcnt lgkmcnt(0)
	v_mfma_f32_16x16x32_bf16 v[22:25], v[228:231], v[236:239], v[22:25]
	global_load_dword v156, v96, s[54:55] offset:2048
	s_add_u32 s52, s52, s56
	s_addc_u32 s53, s53, s57
	s_add_u32 s54, s54, s56
	s_addc_u32 s55, s55, s57
	s_and_saveexec_b64 s[16:17], s[0:1]
	s_nop 6
	v_cvt_pk_bf16_f32 v46, v22, v23
	v_cvt_pk_bf16_f32 v47, v24, v25
	ds_write_b64 v172, v[46:47] offset:34880
	s_or_b64 exec, exec, s[16:17]
	global_load_dword v48, v73, s[62:63] offset:32
	s_and_b64 vcc, exec, s[10:11]
	s_cbranch_vccnz .Lml_wh0_a
	s_waitcnt vmcnt(39)
	s_branch .Lml_wh0_b

.Lml_wh0_b:
	ds_bpermute_b32 v228, v109, v207
	s_waitcnt lgkmcnt(0)
	s_barrier
	s_and_b64 vcc, exec, s[4:5]
	s_cbranch_vccnz .LBB0_469
	v_cvt_pk_bf16_f32 v46, v69, s0
	ds_write_b16 v72, v46 offset:4608
.LBB0_469:
	v_lshlrev_b32_e32 v46, 16, v154
	ds_write_b32 v209, v151
	ds_write2_b32 v208, v153, v157 offset1:132
	ds_write2_b32 v210, v159, v161 offset0:8 offset1:140
	ds_write2_b32 v211, v164, v169 offset0:16 offset1:148
	ds_write2_b32 v213, v180, v190 offset0:24 offset1:156
	ds_write2_b32 v214, v192, v194 offset0:32 offset1:164
	ds_write2_b32 v215, v196, v198 offset0:40 offset1:172
	ds_write2_b32 v216, v200, v202 offset0:48 offset1:180
	ds_write_b32 v208, v204 offset:7392
	ds_write_b128 v61, v[252:255]
	v_and_or_b32 v208, v152, s43, v46
	v_lshlrev_b32_e32 v46, 16, v160
	v_and_or_b32 v209, v158, s43, v46
	v_lshlrev_b32_e32 v46, 16, v165
	v_and_or_b32 v210, v162, s43, v46
	v_lshlrev_b32_e32 v46, 16, v181
	v_and_or_b32 v211, v171, s43, v46
	v_lshrrev_b32_e32 v46, 16, v152
	v_and_or_b32 v230, v154, s44, v46
	v_lshrrev_b32_e32 v46, 16, v158
	v_and_or_b32 v231, v160, s44, v46
	v_lshrrev_b32_e32 v46, 16, v162
	v_and_or_b32 v232, v165, s44, v46
	v_lshrrev_b32_e32 v46, 16, v171
	v_and_or_b32 v233, v181, s44, v46
	v_lshlrev_b32_e32 v46, 16, v193
	ds_write_b128 v173, v[208:211] offset:33792
	ds_write_b128 v173, v[230:233] offset:33936
	v_and_or_b32 v208, v191, s43, v46
	v_lshlrev_b32_e32 v46, 16, v197
	v_and_or_b32 v209, v195, s43, v46
	v_lshlrev_b32_e32 v46, 16, v201
	v_and_or_b32 v210, v199, s43, v46
	v_lshlrev_b32_e32 v46, 16, v205
	v_and_or_b32 v211, v203, s43, v46
	v_lshrrev_b32_e32 v46, 16, v191
	v_and_or_b32 v230, v193, s44, v46
	v_lshrrev_b32_e32 v46, 16, v195
	v_and_or_b32 v231, v197, s44, v46
	v_lshrrev_b32_e32 v46, 16, v199
	v_and_or_b32 v232, v201, s44, v46
	v_lshrrev_b32_e32 v46, 16, v203
	v_and_or_b32 v233, v205, s44, v46
	s_and_b64 vcc, exec, s[6:7]
	ds_write_b128 v174, v[208:211] offset:33792
	ds_write_b128 v174, v[230:233] offset:33936
	s_cbranch_vccnz .LBB0_471
	v_lshlrev_b32_e32 v46, 16, v127
	v_lshlrev_b32_e32 v47, 16, v128
	v_mul_f32_e32 v46, v58, v46
	v_mul_f32_e32 v47, v59, v47
	v_cvt_pk_bf16_f32 v208, v46, v47
	v_lshlrev_b32_e32 v46, 16, v129
	v_lshlrev_b32_e32 v47, 16, v130
	v_mul_f32_e32 v46, v60, v46
	v_mul_f32_e32 v47, v62, v47
	v_cvt_pk_bf16_f32 v209, v46, v47
	v_lshlrev_b32_e32 v46, 16, v131
	v_lshlrev_b32_e32 v47, 16, v132
	v_mul_f32_e32 v46, v63, v46
	v_mul_f32_e32 v47, v64, v47
	v_cvt_pk_bf16_f32 v210, v46, v47
	v_lshlrev_b32_e32 v46, 16, v133
	v_lshlrev_b32_e32 v47, 16, v175
	v_mul_f32_e32 v46, v65, v46
	v_mul_f32_e32 v47, v68, v47
	v_cvt_pk_bf16_f32 v211, v46, v47
	v_and_b32_e32 v46, 0xffff0000, v127
	v_and_b32_e32 v47, 0xffff0000, v128
	v_mul_f32_e32 v46, v58, v46
	v_mul_f32_e32 v47, v59, v47
	v_cvt_pk_bf16_f32 v230, v46, v47
	v_and_b32_e32 v46, 0xffff0000, v129
	v_and_b32_e32 v47, 0xffff0000, v130
	v_mul_f32_e32 v46, v60, v46
	v_mul_f32_e32 v47, v62, v47
	v_cvt_pk_bf16_f32 v231, v46, v47
	v_and_b32_e32 v46, 0xffff0000, v131
	v_and_b32_e32 v47, 0xffff0000, v132
	v_mul_f32_e32 v46, v63, v46
	v_mul_f32_e32 v47, v64, v47
	v_cvt_pk_bf16_f32 v232, v46, v47
	v_and_b32_e32 v46, 0xffff0000, v133
	v_and_b32_e32 v47, 0xffff0000, v175
	v_mul_f32_e32 v46, v65, v46
	v_mul_f32_e32 v47, v68, v47
	v_cvt_pk_bf16_f32 v233, v46, v47
	ds_write_b128 v166, v[208:211]
	ds_write_b128 v166, v[230:233] offset:144
.LBB0_471:
.LBB0_473:
	s_and_b64 vcc, exec, s[6:7]
	s_cbranch_vccnz .LBB0_476
	global_load_dword v127, v97, s[36:37] nt
	global_load_dword v58, v50, s[38:39]
	global_load_dword v128, v98, s[36:37] nt
	global_load_dword v59, v51, s[38:39]
	global_load_dword v129, v99, s[36:37] nt
	global_load_dword v60, v52, s[38:39]
	global_load_dword v130, v100, s[36:37] nt
	global_load_dword v62, v53, s[38:39]
	global_load_dword v131, v101, s[36:37] nt
	global_load_dword v63, v54, s[38:39]
	global_load_dword v132, v102, s[36:37] nt
	global_load_dword v64, v55, s[38:39]
	global_load_dword v133, v103, s[36:37] nt
	global_load_dword v65, v56, s[38:39]
	global_load_dword v175, v104, s[36:37] nt
	global_load_dword v68, v57, s[38:39]
.LBB0_476:
	s_add_i32 s7, s25, -2
	s_add_i32 s14, s19, 1
	s_and_b64 s[30:31], s[2:3], exec
	s_cselect_b32 s7, s14, s7
	s_max_i32 s7, s7, 0
	s_lshl_b32 s14, s7, 14
	s_mov_b32 s15, s22
	v_lshl_add_u64 v[46:47], v[66:67], 0, s[14:15]
	global_load_dwordx4 v[252:255], v[46:47], off
	global_load_dword v69, v73, s[38:39]
	s_mov_b64 s[62:63], s[38:39]
	s_add_u32 s36, s36, s40
	s_addc_u32 s37, s37, s57
	s_add_u32 s38, s38, s41
	s_addc_u32 s39, s39, s57
.LBB0_480:
	s_waitcnt lgkmcnt(0)
	s_barrier
	ds_read_b128 v[208:211], v187
	v_add_u32_e32 v46, v87, v167
	ds_read_b128 v[212:215], v46
	ds_read_b128 v[230:233], v187 offset:64
	ds_read_b128 v[234:237], v46 offset:64
	ds_read_b128 v[238:241], v88
	ds_read_b128 v[242:245], v88 offset:64
	s_waitcnt lgkmcnt(4)
	v_mfma_f32_16x16x32_bf16 v[212:215], v[208:211], v[212:215], 0
	global_load_dword v151, v89, s[52:53]
	s_waitcnt lgkmcnt(1)
	v_mfma_f32_16x16x32_bf16 v[208:211], v[208:211], v[238:241], 0
	global_load_dword v152, v89, s[52:53] offset:2048
	v_mfma_f32_16x16x32_bf16 v[212:215], v[230:233], v[234:237], v[212:215]
	global_load_dword v153, v89, s[54:55]
	s_waitcnt lgkmcnt(0)
	v_mfma_f32_16x16x32_bf16 v[208:211], v[230:233], v[242:245], v[208:211]
	global_load_dword v154, v89, s[54:55] offset:2048
	ds_read_b128 v[230:233], v187 offset:128
	ds_read_b128 v[234:237], v46 offset:128
	ds_read_b128 v[238:241], v46 offset:192
	ds_read_b128 v[242:245], v187 offset:192
	s_waitcnt lgkmcnt(2)
	v_mfma_f32_16x16x32_bf16 v[212:215], v[230:233], v[234:237], v[212:215]
	global_load_dword v157, v90, s[52:53]
	ds_read_b128 v[234:237], v88 offset:128
	ds_read_b128 v[246:249], v88 offset:192
	s_waitcnt lgkmcnt(1)
	v_mfma_f32_16x16x32_bf16 v[208:211], v[230:233], v[234:237], v[208:211]
	global_load_dword v158, v90, s[52:53] offset:2048
	v_mfma_f32_16x16x32_bf16 v[212:215], v[242:245], v[238:241], v[212:215]
	global_load_dword v159, v90, s[54:55]
	s_waitcnt lgkmcnt(0)
	v_mfma_f32_16x16x32_bf16 v[208:211], v[242:245], v[246:249], v[208:211]
	global_load_dword v160, v90, s[54:55] offset:2048
	ds_read_b128 v[230:233], v187 offset:256
	ds_read_b128 v[234:237], v46 offset:256
	ds_read_b128 v[238:241], v46 offset:320
	ds_read_b128 v[242:245], v187 offset:320
	s_waitcnt lgkmcnt(2)
	v_mfma_f32_16x16x32_bf16 v[212:215], v[230:233], v[234:237], v[212:215]
	global_load_dword v161, v91, s[52:53]
	ds_read_b128 v[234:237], v88 offset:256
	ds_read_b128 v[246:249], v88 offset:320
	s_waitcnt lgkmcnt(1)
	v_mfma_f32_16x16x32_bf16 v[208:211], v[230:233], v[234:237], v[208:211]
	global_load_dword v162, v91, s[52:53] offset:2048
	v_mfma_f32_16x16x32_bf16 v[212:215], v[242:245], v[238:241], v[212:215]
	global_load_dword v164, v91, s[54:55]
	s_waitcnt lgkmcnt(0)
	v_mfma_f32_16x16x32_bf16 v[208:211], v[242:245], v[246:249], v[208:211]
	global_load_dword v165, v91, s[54:55] offset:2048
	ds_read_b128 v[230:233], v187 offset:384
	ds_read_b128 v[234:237], v46 offset:384
	ds_read_b128 v[238:241], v46 offset:448
	ds_read_b128 v[242:245], v187 offset:448
	s_waitcnt lgkmcnt(2)
	v_mfma_f32_16x16x32_bf16 v[212:215], v[230:233], v[234:237], v[212:215]
	global_load_dword v169, v92, s[52:53]
	ds_read_b128 v[234:237], v88 offset:384
	ds_read_b128 v[246:249], v88 offset:448
	s_waitcnt lgkmcnt(1)
	v_mfma_f32_16x16x32_bf16 v[208:211], v[230:233], v[234:237], v[208:211]
	global_load_dword v171, v92, s[52:53] offset:2048
	v_mfma_f32_16x16x32_bf16 v[212:215], v[242:245], v[238:241], v[212:215]
	global_load_dword v180, v92, s[54:55]
	s_waitcnt lgkmcnt(0)
	v_mfma_f32_16x16x32_bf16 v[208:211], v[242:245], v[246:249], v[208:211]
	global_load_dword v181, v92, s[54:55] offset:2048
	ds_bpermute_b32 v46, v176, v207
	ds_bpermute_b32 v47, v177, v207
	ds_bpermute_b32 v216, v178, v207
	ds_bpermute_b32 v207, v179, v207
	ds_read_b128 v[230:233], v188
	ds_read_b128 v[234:237], v218
	s_waitcnt lgkmcnt(5)
	v_mul_f32_e32 v46, 0x3fb8aa3b, v46
	s_waitcnt lgkmcnt(4)
	v_mul_f32_e32 v47, 0x3fb8aa3b, v47
	s_waitcnt lgkmcnt(3)
	v_mul_f32_e32 v216, 0x3fb8aa3b, v216
	s_waitcnt lgkmcnt(2)
	v_mul_f32_e32 v207, 0x3fb8aa3b, v207
	v_exp_f32_e32 v46, v46
	v_exp_f32_e32 v47, v47
	v_exp_f32_e32 v246, v216
	v_exp_f32_e32 v247, v207
	ds_read_b128 v[238:241], v206
	ds_read_b128 v[242:245], v188 offset:64
	v_pk_mul_f32 v[212:213], v[212:213], v[46:47]
	v_pk_mul_f32 v[208:209], v[208:209], v[46:47]
	v_pk_mul_f32 v[214:215], v[214:215], v[246:247]
	v_pk_mul_f32 v[210:211], v[210:211], v[246:247]
	v_add_u32_e32 v47, 64, v217
	s_waitcnt lgkmcnt(2)
	v_mfma_f32_16x16x32_bf16 v[212:215], v[230:233], v[234:237], v[212:215]
	global_load_dword v190, v93, s[52:53]
	s_waitcnt lgkmcnt(1)
	v_mfma_f32_16x16x32_bf16 v[208:211], v[230:233], v[238:241], v[208:211]
	global_load_dword v191, v93, s[52:53] offset:2048
	ds_read_b128 v[230:233], v110
	ds_read_b128 v[234:237], v219
	s_waitcnt lgkmcnt(1)
	v_mfma_f32_16x16x32_bf16 v[208:211], v[242:245], v[230:233], v[208:211]
	global_load_dword v192, v93, s[54:55]
	s_waitcnt lgkmcnt(0)
	v_mfma_f32_16x16x32_bf16 v[212:215], v[242:245], v[234:237], v[212:215]
	global_load_dword v193, v93, s[54:55] offset:2048
	s_nop 5
	ds_bpermute_b32 v46, v170, v208
	s_waitcnt lgkmcnt(0)
	v_max_f32_e64 v46, |v46|, |v46|
	v_max_f32_e32 v207, 1.0, v46
	v_div_scale_f32 v208, s[4:5], v207, v207, v212
	v_rcp_f32_e32 v216, v208
	v_subrev_u32_e32 v46, 64, v222
	v_cndmask_b32_e64 v46, v46, v47, s[2:3]
	v_ashrrev_i32_e32 v47, 31, v46
	v_fma_f32 v218, -v208, v216, 1.0
	v_fmac_f32_e32 v216, v218, v216
	v_div_scale_f32 v218, vcc, v212, v207, v212
	v_mul_f32_e32 v219, v218, v216
	v_fma_f32 v229, -v208, v219, v218
	v_fmac_f32_e32 v219, v229, v216
	v_fma_f32 v208, -v208, v219, v218
	v_div_fmas_f32 v208, v208, v216, v219
	v_div_fixup_f32 v207, v208, v207, v212
	ds_bpermute_b32 v208, v170, v209
	v_lshlrev_b64 v[46:47], 12, v[46:47]
	v_cvt_pk_bf16_f32 v207, v207, s0
	v_lshl_add_u64 v[46:47], v[70:71], 0, v[46:47]
	global_store_short v[46:47], v207, off offset:2048
	s_waitcnt lgkmcnt(0)
	v_max_f32_e64 v47, |v208|, |v208|
	v_max_f32_e32 v207, 1.0, v47
	v_div_scale_f32 v208, s[4:5], v207, v207, v213
	v_rcp_f32_e32 v209, v208
	v_add_u32_e32 v46, 0xffffffbf, v222
	v_add_u32_e32 v47, 0x41, v217
	v_cndmask_b32_e64 v46, v46, v47, s[2:3]
	v_fma_f32 v212, -v208, v209, 1.0
	v_fmac_f32_e32 v209, v212, v209
	v_div_scale_f32 v212, vcc, v213, v207, v213
	v_mul_f32_e32 v216, v212, v209
	v_fma_f32 v218, -v208, v216, v212
	v_fmac_f32_e32 v216, v218, v209
	v_fma_f32 v208, -v208, v216, v212
	v_div_fmas_f32 v208, v208, v209, v216
	v_div_fixup_f32 v207, v208, v207, v213
	ds_bpermute_b32 v208, v170, v210
	v_ashrrev_i32_e32 v47, 31, v46
	v_lshlrev_b64 v[46:47], 12, v[46:47]
	v_cvt_pk_bf16_f32 v207, v207, s0
	v_lshl_add_u64 v[46:47], v[70:71], 0, v[46:47]
	global_store_short v[46:47], v207, off offset:2048
	s_waitcnt lgkmcnt(0)
	v_max_f32_e64 v47, |v208|, |v208|
	v_max_f32_e32 v207, 1.0, v47
	v_div_scale_f32 v208, s[4:5], v207, v207, v214
	v_rcp_f32_e32 v209, v208
	v_add_u32_e32 v46, 0xfbd, v223
	v_add_u32_e32 v47, 0x42, v217
	v_cndmask_b32_e64 v46, v46, v47, s[2:3]
	v_fma_f32 v210, -v208, v209, 1.0
	v_fmac_f32_e32 v209, v210, v209
	v_div_scale_f32 v210, vcc, v214, v207, v214
	v_mul_f32_e32 v212, v210, v209
	v_fma_f32 v213, -v208, v212, v210
	v_fmac_f32_e32 v212, v213, v209
	v_fma_f32 v208, -v208, v212, v210
	v_div_fmas_f32 v208, v208, v209, v212
	v_div_fixup_f32 v207, v208, v207, v214
	ds_bpermute_b32 v208, v170, v211
	v_ashrrev_i32_e32 v47, 31, v46
	v_lshlrev_b64 v[46:47], 12, v[46:47]
	v_cvt_pk_bf16_f32 v207, v207, s0
	v_lshl_add_u64 v[46:47], v[70:71], 0, v[46:47]
	global_store_short v[46:47], v207, off offset:2048
	s_waitcnt lgkmcnt(0)
	v_max_f32_e64 v46, |v208|, |v208|
	ds_read_b128 v[208:211], v224 offset:33792
	v_max_f32_e32 v212, 1.0, v46
	v_mul_f32_e32 v46, 0x3fb8aa3b, v228
	v_exp_f32_e32 v46, v46
	v_add_u32_e32 v207, 0x43, v217
	ds_read_b128 v[216:219], v111
	ds_read_b128 v[228:231], v49 offset:33792
	v_add_u32_e32 v47, 0xfbc, v223
	v_pk_mul_f32 v[44:45], v[44:45], v[46:47] op_sel_hi:[1,0]
	v_pk_mul_f32 v[42:43], v[42:43], v[46:47] op_sel_hi:[1,0]
	ds_read_b128 v[232:235], v225
	v_div_scale_f32 v213, s[4:5], v212, v212, v215
	s_waitcnt lgkmcnt(2)
	v_mfma_f32_16x16x32_bf16 v[42:45], v[208:211], v[216:219], v[42:45]
	global_load_dword v194, v94, s[52:53]
	v_rcp_f32_e32 v214, v213
	v_cndmask_b32_e64 v222, v47, v207, s[2:3]
	v_ashrrev_i32_e32 v223, 31, v222
	s_waitcnt lgkmcnt(0)
	v_mfma_f32_16x16x32_bf16 v[42:45], v[228:231], v[232:235], v[42:45]
	global_load_dword v195, v94, s[52:53] offset:2048
	v_fma_f32 v47, -v213, v214, 1.0
	v_fmac_f32_e32 v214, v47, v214
	v_div_scale_f32 v47, vcc, v215, v212, v215
	v_pk_mul_f32 v[40:41], v[40:41], v[46:47] op_sel_hi:[1,0]
	s_nop 3
	v_cvt_pk_bf16_f32 v208, v42, v43
	v_cvt_pk_bf16_f32 v209, v44, v45
	ds_write_b64 v189, v[208:209]
	ds_read_b128 v[208:211], v49 offset:33792
	ds_read_b128 v[216:219], v224 offset:33792
	ds_read_b128 v[228:231], v226
	ds_read_b128 v[232:235], v227
	v_pk_mul_f32 v[38:39], v[38:39], v[46:47] op_sel_hi:[1,0]
	v_mul_f32_e32 v207, v47, v214
	s_waitcnt lgkmcnt(1)
	v_mfma_f32_16x16x32_bf16 v[38:41], v[216:219], v[228:231], v[38:41]
	global_load_dword v196, v94, s[54:55]
	v_fma_f32 v216, -v213, v207, v47
	v_fmac_f32_e32 v207, v216, v214
	v_fma_f32 v47, -v213, v207, v47
	s_waitcnt lgkmcnt(0)
	v_mfma_f32_16x16x32_bf16 v[38:41], v[208:211], v[232:235], v[38:41]
	global_load_dword v197, v94, s[54:55] offset:2048
	v_div_fmas_f32 v47, v47, v214, v207
	v_div_fixup_f32 v47, v47, v212, v215
	v_cvt_pk_bf16_f32 v47, v47, s0
	v_pk_mul_f32 v[36:37], v[36:37], v[46:47] op_sel_hi:[1,0]
	v_pk_mul_f32 v[34:35], v[34:35], v[46:47] op_sel_hi:[1,0]
	s_nop 2
	v_cvt_pk_bf16_f32 v208, v38, v39
	v_cvt_pk_bf16_f32 v209, v40, v41
	ds_write_b64 v189, v[208:209] offset:8448
	ds_read_b128 v[208:211], v49 offset:33792
	ds_read_b128 v[216:219], v224 offset:33792
	ds_read_b128 v[212:215], v206
	ds_read_b128 v[228:231], v110
	s_waitcnt lgkmcnt(1)
	v_mfma_f32_16x16x32_bf16 v[34:37], v[216:219], v[212:215], v[34:37]
	global_load_dword v198, v95, s[52:53]
	v_lshlrev_b64 v[212:213], 12, v[222:223]
	v_lshl_add_u64 v[212:213], v[70:71], 0, v[212:213]
	global_store_short v[212:213], v47, off offset:2048
	s_waitcnt lgkmcnt(0)
	v_mfma_f32_16x16x32_bf16 v[34:37], v[208:211], v[228:231], v[34:37]
	global_load_dword v199, v95, s[52:53] offset:2048
	s_and_saveexec_b64 s[4:5], s[0:1]
	s_nop 6
	v_cvt_pk_bf16_f32 v208, v34, v35
	v_cvt_pk_bf16_f32 v209, v36, v37
	ds_write_b64 v172, v[208:209] offset:16896
	s_or_b64 exec, exec, s[4:5]
	ds_read_b128 v[208:211], v224 offset:36096
	ds_read_b128 v[212:215], v111
	ds_read_b128 v[216:219], v49 offset:36096
	v_mov_b32_e32 v47, v46
	v_mov_b32_e32 v222, v46
	v_mov_b32_e32 v223, v46
	v_pk_mul_f32 v[28:29], v[28:29], v[222:223]
	v_pk_mul_f32 v[26:27], v[26:27], v[46:47]
	v_pk_mul_f32 v[32:33], v[32:33], v[222:223]
	v_pk_mul_f32 v[30:31], v[30:31], v[46:47]
	s_waitcnt lgkmcnt(1)
	v_mfma_f32_16x16x32_bf16 v[26:29], v[208:211], v[212:215], v[26:29]
	global_load_dword v200, v95, s[54:55]
	ds_read_b128 v[208:211], v225
	v_pk_mul_f32 v[24:25], v[24:25], v[222:223]
	v_pk_mul_f32 v[22:23], v[22:23], v[46:47]
	s_waitcnt lgkmcnt(0)
	v_mfma_f32_16x16x32_bf16 v[26:29], v[216:219], v[208:211], v[26:29]
	global_load_dword v201, v95, s[54:55] offset:2048
	s_nop 7
	v_cvt_pk_bf16_f32 v208, v26, v27
	v_cvt_pk_bf16_f32 v209, v28, v29
	ds_write_b64 v189, v[208:209] offset:32
	ds_read_b128 v[208:211], v224 offset:36096
	ds_read_b128 v[212:215], v226
	ds_read_b128 v[216:219], v49 offset:36096
	ds_read_b128 v[226:229], v227
	s_waitcnt lgkmcnt(2)
	v_mfma_f32_16x16x32_bf16 v[30:33], v[208:211], v[212:215], v[30:33]
	global_load_dword v202, v96, s[52:53]
	s_waitcnt lgkmcnt(0)
	v_mfma_f32_16x16x32_bf16 v[30:33], v[216:219], v[226:229], v[30:33]
	global_load_dword v203, v96, s[52:53] offset:2048
	s_nop 7
	v_cvt_pk_bf16_f32 v208, v30, v31
	v_cvt_pk_bf16_f32 v209, v32, v33
	ds_write_b64 v189, v[208:209] offset:8480
	ds_read_b128 v[208:211], v224 offset:36096
	ds_read_b128 v[212:215], v206
	ds_read_b128 v[216:219], v49 offset:36096
	ds_read_b128 v[222:225], v110
	s_waitcnt lgkmcnt(2)
	v_mfma_f32_16x16x32_bf16 v[22:25], v[208:211], v[212:215], v[22:25]
	global_load_dword v204, v96, s[54:55]
	s_waitcnt lgkmcnt(0)
	v_mfma_f32_16x16x32_bf16 v[22:25], v[216:219], v[222:225], v[22:25]
	global_load_dword v205, v96, s[54:55] offset:2048
	s_add_u32 s52, s52, s56
	s_addc_u32 s53, s53, s57
	s_add_u32 s54, s54, s56
	s_addc_u32 s55, s55, s57
	global_load_dword v207, v73, s[62:63] offset:32
	s_and_saveexec_b64 s[4:5], s[0:1]
	s_cbranch_execz .LBB0_452
	s_nop 5
	v_cvt_pk_bf16_f32 v46, v22, v23
	v_cvt_pk_bf16_f32 v47, v24, v25
	ds_write_b64 v172, v[46:47] offset:16928
	s_branch .LBB0_452

	.amdhsa_kernel _Z6mk_fwd4Args
		.amdhsa_group_segment_fixed_size 0
		.amdhsa_private_segment_fixed_size 0
		.amdhsa_kernarg_size 456
		.amdhsa_user_sgpr_count 2
		.amdhsa_user_sgpr_dispatch_ptr 0
		.amdhsa_user_sgpr_queue_ptr 0
		.amdhsa_user_sgpr_kernarg_segment_ptr 1
		.amdhsa_user_sgpr_dispatch_id 0
		.amdhsa_user_sgpr_kernarg_preload_length 0
		.amdhsa_user_sgpr_kernarg_preload_offset 0
		.amdhsa_user_sgpr_private_segment_size 0
		.amdhsa_uses_dynamic_stack 0
		.amdhsa_enable_private_segment 0
		.amdhsa_system_sgpr_workgroup_id_x 1
		.amdhsa_system_sgpr_workgroup_id_y 0
		.amdhsa_system_sgpr_workgroup_id_z 0
		.amdhsa_system_sgpr_workgroup_info 0
		.amdhsa_system_vgpr_workitem_id 2
		.amdhsa_next_free_vgpr 256
		.amdhsa_next_free_sgpr 100
		.amdhsa_accum_offset 256
		.amdhsa_reserve_vcc 1
		.amdhsa_float_round_mode_32 0
		.amdhsa_float_round_mode_16_64 0
		.amdhsa_float_denorm_mode_32 3
		.amdhsa_float_denorm_mode_16_64 3
		.amdhsa_dx10_clamp 1
		.amdhsa_ieee_mode 1
		.amdhsa_fp16_overflow 0
		.amdhsa_tg_split 0
		.amdhsa_exception_fp_ieee_invalid_op 0
		.amdhsa_exception_fp_denorm_src 0
		.amdhsa_exception_fp_ieee_div_zero 0
		.amdhsa_exception_fp_ieee_overflow 0
		.amdhsa_exception_fp_ieee_underflow 0
		.amdhsa_exception_fp_ieee_inexact 0
		.amdhsa_exception_int_div_zero 0
	.end_amdhsa_kernel

.Lfunc_end0:
	.size	_Z6mk_fwd4Args, .Lfunc_end0-_Z6mk_fwd4Args
	.set _Z6mk_fwd4Args.num_vgpr, 256
	.set _Z6mk_fwd4Args.num_agpr, 0
	.set _Z6mk_fwd4Args.numbered_sgpr, 100
	.set _Z6mk_fwd4Args.num_named_barrier, 0
	.set _Z6mk_fwd4Args.private_seg_size, 0
	.set _Z6mk_fwd4Args.uses_vcc, 1
	.set _Z6mk_fwd4Args.uses_flat_scratch, 0
	.set _Z6mk_fwd4Args.has_dyn_sized_stack, 0
	.set _Z6mk_fwd4Args.has_recursion, 0
	.set _Z6mk_fwd4Args.has_indirect_call, 0

amdhsa.kernels:
  - .agpr_count:     0
    .args:
      - .offset:         0
        .size:           200
        .value_kind:     by_value
      - .offset:         200
        .size:           4
        .value_kind:     hidden_block_count_x
      - .offset:         204
        .size:           4
        .value_kind:     hidden_block_count_y
      - .offset:         208
        .size:           4
        .value_kind:     hidden_block_count_z
      - .offset:         212
        .size:           2
        .value_kind:     hidden_group_size_x
      - .offset:         214
        .size:           2
        .value_kind:     hidden_group_size_y
      - .offset:         216
        .size:           2
        .value_kind:     hidden_group_size_z
      - .offset:         218
        .size:           2
        .value_kind:     hidden_remainder_x
      - .offset:         220
        .size:           2
        .value_kind:     hidden_remainder_y
      - .offset:         222
        .size:           2
        .value_kind:     hidden_remainder_z
      - .offset:         240
        .size:           8
        .value_kind:     hidden_global_offset_x
      - .offset:         248
        .size:           8
        .value_kind:     hidden_global_offset_y
      - .offset:         256
        .size:           8
        .value_kind:     hidden_global_offset_z
      - .offset:         264
        .size:           2
        .value_kind:     hidden_grid_dims
      - .offset:         288
        .size:           8
        .value_kind:     hidden_multigrid_sync_arg
      - .offset:         320
        .size:           4
        .value_kind:     hidden_dynamic_lds_size
    .group_segment_fixed_size: 0
    .kernarg_segment_align: 8
    .kernarg_segment_size: 456
    .language:       OpenCL C
    .language_version:
      - 2
      - 0
    .max_flat_workgroup_size: 512
    .name:           _Z6mk_fwd4Args
    .private_segment_fixed_size: 0
    .sgpr_count:     106
    .sgpr_spill_count: 87
    .symbol:         _Z6mk_fwd4Args.kd
    .uniform_work_group_size: 1
    .uses_dynamic_stack: false
    .vgpr_count:     256
    .vgpr_spill_count: 0
    .wavefront_size: 64
